# v13 + gate/up K-loop first iteration peeled (prefetch drained before epilogue stores, first two counted waits dropped)
# speedup vs baseline: 1.0187x; 1.0187x over previous
.LBB0_140:
	s_add_u32 s8, s4, 0xc200000
	s_addc_u32 s9, s5, 0
	s_and_b32 s14, s10, 3
	s_add_i32 m0, s40, 0x18000
	v_lshl_add_u64 v[6:7], v[6:7], 0, s[64:65]
	s_lshl_b32 s11, s3, 13
	s_lshl_b32 s15, s14, 5
	s_lshl_b32 s16, s14, 12
	s_waitcnt vmcnt(2)
	s_barrier
	global_load_lds_dwordx4 v[6:7], off
	v_lshl_add_u64 v[4:5], v[4:5], 0, s[64:65]
	s_add_i32 m0, s40, 0x1a000
	s_add_i32 s44, s40, 0x8000
	s_add_i32 s45, s40, 0xa000
	global_load_lds_dwordx4 v[4:5], off
	v_lshl_add_u64 v[0:1], v[0:1], 0, s[64:65]
	s_mov_b32 m0, s44
	s_add_u32 s12, s26, 0x40080
	global_load_lds_dwordx4 v[0:1], off
	v_lshl_add_u64 v[0:1], v[2:3], 0, s[64:65]
	s_mov_b32 m0, s45
	s_addc_u32 s13, s27, 0
	global_load_lds_dwordx4 v[0:1], off
	s_add_i32 m0, s40, 0x1c000
	v_lshl_add_u64 v[0:1], s[12:13], 0, v[96:97]
	global_load_lds_dwordx4 v[0:1], off
	v_lshl_add_u64 v[0:1], s[12:13], 0, v[130:131]
	s_add_i32 m0, s40, 0x1e000
	s_cmp_lt_u32 s10, 4
	global_load_lds_dwordx4 v[0:1], off
	v_and_b32_e32 v0, 15, v8
	v_bfe_u32 v1, v8, 4, 2
	v_lshlrev_b32_e32 v2, 4, v1
	v_lshlrev_b32_e32 v4, 2, v0
	v_lshl_or_b32 v3, v0, 6, v2
	v_and_b32_e32 v5, 32, v4
	s_sext_i32_i16 s23, s2
	v_bitop3_b32 v6, v3, s11, v5 bitop3:0xde
	v_lshl_or_b32 v144, v1, 3, s15
	s_cselect_b64 s[10:11], -1, 0
	s_lshl_b32 s2, s3, 8
	v_lshl_or_b32 v1, s14, 6, v2
	v_or_b32_e32 v1, s2, v1
	v_lshl_or_b32 v142, s3, 6, v0
	v_or_b32_e32 v2, v1, v0
	v_bitop3_b32 v145, v1, s92, v0 bitop3:0xc8
	v_lshlrev_b32_e32 v0, 14, v13
	v_and_b32_e32 v0, 0xffff8000, v0
	v_lshl_add_u32 v0, v12, 11, v0
	v_and_b32_e32 v1, 1, v13
	v_lshl_or_b32 v0, v1, 6, v0
	v_lshl_add_u32 v136, v14, 1, v0
	v_lshlrev_b32_e32 v0, 14, v9
	v_and_b32_e32 v0, 0xffff8000, v0
	s_waitcnt vmcnt(6)
	s_cmp_eq_u32 s2, 0
	v_lshl_add_u32 v0, v10, 11, v0
	v_and_b32_e32 v1, 1, v9
	s_cselect_b64 s[12:13], -1, 0
	s_add_i32 s2, s93, s2
	v_lshl_or_b32 v0, v1, 6, v0
	v_bitop3_b32 v143, v3, s16, v5 bitop3:0xde
	s_mov_b32 s47, 0
	v_add_u32_e32 v146, s2, v4
	v_lshl_add_u32 v147, v2, 2, s93
	v_mov_b32_e32 v137, v97
	v_lshl_add_u32 v138, v11, 1, v0
	v_mov_b32_e32 v139, v97
	v_add_u32_e32 v148, 0, v6
	s_waitcnt vmcnt(0)
	s_barrier
	s_branch .LBB0_143

.LBB0_145:
	s_ashr_i32 s17, s16, 31
	s_lshl_b64 s[18:19], s[16:17], 19
	s_add_u32 s18, s36, s18
	s_addc_u32 s19, s37, s19
	s_and_b64 s[20:21], s[2:3], exec
	s_cselect_b32 s17, s19, s25
	s_cselect_b32 s50, s18, s24
	s_ashr_i32 s15, s14, 31
	s_lshl_b64 s[20:21], s[14:15], 19
	s_add_u32 s20, s34, s20
	s_addc_u32 s21, s35, s21
	s_and_b64 s[28:29], s[2:3], exec
	s_cselect_b32 s15, s21, s27
	s_cselect_b32 s51, s20, s26
	s_add_u32 s24, s24, 0x40080
	s_addc_u32 s25, s25, 0
	s_add_u32 s52, s26, 0x100
	v_mov_b32_e32 v0, 0
	s_addc_u32 s53, s27, 0
	s_mov_b32 s54, -2
	v_mov_b32_e32 v1, v0
	v_mov_b32_e32 v2, v0
	v_mov_b32_e32 v3, v0
	v_mov_b32_e32 v8, v0
	v_mov_b32_e32 v9, v0
	v_mov_b32_e32 v10, v0
	v_mov_b32_e32 v11, v0
	v_mov_b32_e32 v16, v0
	v_mov_b32_e32 v17, v0
	v_mov_b32_e32 v18, v0
	v_mov_b32_e32 v19, v0
	v_mov_b32_e32 v24, v0
	v_mov_b32_e32 v25, v0
	v_mov_b32_e32 v26, v0
	v_mov_b32_e32 v27, v0
	v_mov_b32_e32 v32, v0
	v_mov_b32_e32 v33, v0
	v_mov_b32_e32 v34, v0
	v_mov_b32_e32 v35, v0
	v_mov_b32_e32 v40, v0
	v_mov_b32_e32 v41, v0
	v_mov_b32_e32 v42, v0
	v_mov_b32_e32 v43, v0
	v_mov_b32_e32 v48, v0
	v_mov_b32_e32 v49, v0
	v_mov_b32_e32 v50, v0
	v_mov_b32_e32 v51, v0
	v_mov_b32_e32 v56, v0
	v_mov_b32_e32 v57, v0
	v_mov_b32_e32 v58, v0
	v_mov_b32_e32 v59, v0
	v_mov_b32_e32 v4, v0
	v_mov_b32_e32 v5, v0
	v_mov_b32_e32 v6, v0
	v_mov_b32_e32 v7, v0
	v_mov_b32_e32 v12, v0
	v_mov_b32_e32 v13, v0
	v_mov_b32_e32 v14, v0
	v_mov_b32_e32 v15, v0
	v_mov_b32_e32 v20, v0
	v_mov_b32_e32 v21, v0
	v_mov_b32_e32 v22, v0
	v_mov_b32_e32 v23, v0
	v_mov_b32_e32 v28, v0
	v_mov_b32_e32 v29, v0
	v_mov_b32_e32 v30, v0
	v_mov_b32_e32 v31, v0
	v_mov_b32_e32 v36, v0
	v_mov_b32_e32 v37, v0
	v_mov_b32_e32 v38, v0
	v_mov_b32_e32 v39, v0
	v_mov_b32_e32 v44, v0
	v_mov_b32_e32 v45, v0
	v_mov_b32_e32 v46, v0
	v_mov_b32_e32 v47, v0
	v_mov_b32_e32 v52, v0
	v_mov_b32_e32 v53, v0
	v_mov_b32_e32 v54, v0
	v_mov_b32_e32 v55, v0
	v_mov_b32_e32 v60, v0
	v_mov_b32_e32 v61, v0
	v_mov_b32_e32 v62, v0
	v_mov_b32_e32 v63, v0
	v_mov_b32_e32 v64, v0
	v_mov_b32_e32 v65, v0
	v_mov_b32_e32 v66, v0
	v_mov_b32_e32 v67, v0
	v_mov_b32_e32 v72, v0
	v_mov_b32_e32 v73, v0
	v_mov_b32_e32 v74, v0
	v_mov_b32_e32 v75, v0
	v_mov_b32_e32 v80, v0
	v_mov_b32_e32 v81, v0
	v_mov_b32_e32 v82, v0
	v_mov_b32_e32 v83, v0
	v_mov_b32_e32 v88, v0
	v_mov_b32_e32 v89, v0
	v_mov_b32_e32 v90, v0
	v_mov_b32_e32 v91, v0
	v_mov_b32_e32 v98, v0
	v_mov_b32_e32 v99, v0
	v_mov_b32_e32 v100, v0
	v_mov_b32_e32 v101, v0
	v_mov_b32_e32 v106, v0
	v_mov_b32_e32 v107, v0
	v_mov_b32_e32 v108, v0
	v_mov_b32_e32 v109, v0
	v_mov_b32_e32 v114, v0
	v_mov_b32_e32 v115, v0
	v_mov_b32_e32 v116, v0
	v_mov_b32_e32 v117, v0
	v_mov_b32_e32 v122, v0
	v_mov_b32_e32 v123, v0
	v_mov_b32_e32 v124, v0
	v_mov_b32_e32 v125, v0
	v_mov_b32_e32 v68, v0
	v_mov_b32_e32 v69, v0
	v_mov_b32_e32 v70, v0
	v_mov_b32_e32 v71, v0
	v_mov_b32_e32 v76, v0
	v_mov_b32_e32 v77, v0
	v_mov_b32_e32 v78, v0
	v_mov_b32_e32 v79, v0
	v_mov_b32_e32 v84, v0
	v_mov_b32_e32 v85, v0
	v_mov_b32_e32 v86, v0
	v_mov_b32_e32 v87, v0
	v_mov_b32_e32 v92, v0
	v_mov_b32_e32 v93, v0
	v_mov_b32_e32 v94, v0
	v_mov_b32_e32 v95, v0
	v_mov_b32_e32 v102, v0
	v_mov_b32_e32 v103, v0
	v_mov_b32_e32 v104, v0
	v_mov_b32_e32 v105, v0
	v_mov_b32_e32 v110, v0
	v_mov_b32_e32 v111, v0
	v_mov_b32_e32 v112, v0
	v_mov_b32_e32 v113, v0
	v_mov_b32_e32 v118, v0
	v_mov_b32_e32 v119, v0
	v_mov_b32_e32 v120, v0
	v_mov_b32_e32 v121, v0
	v_mov_b32_e32 v126, v0
	v_mov_b32_e32 v127, v0
	v_mov_b32_e32 v128, v0
	v_mov_b32_e32 v129, v0
	s_add_u32 s26, s24, 0xfffc0080
	s_addc_u32 s27, s25, -1
	s_add_i32 s55, 0, 0x10000
	s_cmp_eq_u32 s54, 12
	s_cselect_b32 s29, s17, s27
	s_cselect_b32 s28, s50, s26
	v_add_u32_e32 v140, s55, v143
	s_cselect_b32 s27, s15, s53
	s_cselect_b32 s26, s51, s52
	s_add_i32 s60, 0, 0x14000
	ds_read_b128 v[150:153], v140
	ds_read_b128 v[154:157], v140 offset:1024
	ds_read_b128 v[158:161], v140 offset:2048
	ds_read_b128 v[162:165], v140 offset:3072
	v_add_u32_e32 v140, s60, v143
	ds_read_b128 v[166:169], v140
	ds_read_b128 v[170:173], v140 offset:1024
	ds_read_b128 v[174:177], v140 offset:2048
	ds_read_b128 v[178:181], v140 offset:3072
	v_lshl_add_u64 v[140:141], s[24:25], 0, v[136:137]
	s_add_i32 m0, s40, 0xc000
	ds_read_b128 v[182:185], v148
	ds_read_b128 v[186:189], v148 offset:1024
	ds_read_b128 v[190:193], v148 offset:2048
	ds_read_b128 v[202:205], v148 offset:3072
	ds_read_b128 v[206:209], v148 offset:4096
	ds_read_b128 v[210:213], v148 offset:5120
	ds_read_b128 v[214:217], v148 offset:6144
	ds_read_b128 v[218:221], v148 offset:7168
	global_load_lds_dwordx4 v[140:141], off
	v_lshl_add_u64 v[140:141], s[24:25], 0, v[138:139]
	s_add_i32 m0, s40, 0xe000
	s_nop 0
	global_load_lds_dwordx4 v[140:141], off
	s_waitcnt lgkmcnt(0)
	s_barrier
	s_setprio 1
	s_waitcnt lgkmcnt(0)
	v_mfma_f32_16x16x32_bf16 v[126:129], v[150:153], v[182:185], v[126:129]
	v_mfma_f32_16x16x32_bf16 v[118:121], v[158:161], v[182:185], v[118:121]
	v_mfma_f32_16x16x32_bf16 v[110:113], v[150:153], v[190:193], v[110:113]
	v_mfma_f32_16x16x32_bf16 v[102:105], v[158:161], v[190:193], v[102:105]
	v_mfma_f32_16x16x32_bf16 v[92:95], v[150:153], v[206:209], v[92:95]
	v_mfma_f32_16x16x32_bf16 v[84:87], v[158:161], v[206:209], v[84:87]
	v_mfma_f32_16x16x32_bf16 v[76:79], v[150:153], v[214:217], v[76:79]
	v_mfma_f32_16x16x32_bf16 v[68:71], v[158:161], v[214:217], v[68:71]
	v_mfma_f32_16x16x32_bf16 v[126:129], v[154:157], v[186:189], v[126:129]
	v_mfma_f32_16x16x32_bf16 v[118:121], v[162:165], v[186:189], v[118:121]
	v_mfma_f32_16x16x32_bf16 v[110:113], v[154:157], v[202:205], v[110:113]
	v_mfma_f32_16x16x32_bf16 v[102:105], v[162:165], v[202:205], v[102:105]
	v_mfma_f32_16x16x32_bf16 v[92:95], v[154:157], v[210:213], v[92:95]
	v_mfma_f32_16x16x32_bf16 v[84:87], v[162:165], v[210:213], v[84:87]
	v_mfma_f32_16x16x32_bf16 v[76:79], v[154:157], v[218:221], v[76:79]
	v_mfma_f32_16x16x32_bf16 v[68:71], v[162:165], v[218:221], v[68:71]
	s_setprio 0
	s_setprio 1
	v_mfma_f32_16x16x32_bf16 v[122:125], v[166:169], v[182:185], v[122:125]
	v_mfma_f32_16x16x32_bf16 v[114:117], v[174:177], v[182:185], v[114:117]
	v_mfma_f32_16x16x32_bf16 v[106:109], v[166:169], v[190:193], v[106:109]
	v_mfma_f32_16x16x32_bf16 v[98:101], v[174:177], v[190:193], v[98:101]
	v_mfma_f32_16x16x32_bf16 v[88:91], v[166:169], v[206:209], v[88:91]
	v_mfma_f32_16x16x32_bf16 v[80:83], v[174:177], v[206:209], v[80:83]
	v_mfma_f32_16x16x32_bf16 v[72:75], v[166:169], v[214:217], v[72:75]
	v_mfma_f32_16x16x32_bf16 v[64:67], v[174:177], v[214:217], v[64:67]
	v_mfma_f32_16x16x32_bf16 v[122:125], v[170:173], v[186:189], v[122:125]
	v_mfma_f32_16x16x32_bf16 v[114:117], v[178:181], v[186:189], v[114:117]
	v_mfma_f32_16x16x32_bf16 v[106:109], v[170:173], v[202:205], v[106:109]
	v_mfma_f32_16x16x32_bf16 v[98:101], v[178:181], v[202:205], v[98:101]
	v_mfma_f32_16x16x32_bf16 v[88:91], v[170:173], v[210:213], v[88:91]
	v_mfma_f32_16x16x32_bf16 v[80:83], v[178:181], v[210:213], v[80:83]
	v_mfma_f32_16x16x32_bf16 v[72:75], v[170:173], v[218:221], v[72:75]
	v_mfma_f32_16x16x32_bf16 v[64:67], v[178:181], v[218:221], v[64:67]
	s_setprio 0
	s_barrier
	s_add_i32 s55, s55, s39
	v_lshl_add_u64 v[140:141], s[26:27], 0, v[96:97]
	s_mov_b32 m0, s55
	ds_read_b128 v[182:185], v148 offset:16384
	ds_read_b128 v[186:189], v148 offset:17408
	ds_read_b128 v[190:193], v148 offset:18432
	ds_read_b128 v[202:205], v148 offset:19456
	ds_read_b128 v[206:209], v148 offset:20480
	ds_read_b128 v[210:213], v148 offset:21504
	ds_read_b128 v[214:217], v148 offset:22528
	ds_read_b128 v[218:221], v148 offset:23552
	global_load_lds_dwordx4 v[140:141], off
	s_add_i32 m0, s55, 0x2000
	s_add_u32 s56, s26, 0x40000
	v_lshl_add_u64 v[194:195], s[26:27], 0, v[130:131]
	s_addc_u32 s57, s27, 0
	s_add_i32 s55, s60, s39
	global_load_lds_dwordx4 v[194:195], off
	v_lshl_add_u64 v[196:197], s[56:57], 0, v[96:97]
	s_mov_b32 m0, s55
	v_lshl_add_u64 v[198:199], s[28:29], 0, v[132:133]
	global_load_lds_dwordx4 v[196:197], off
	v_lshl_add_u64 v[196:197], s[56:57], 0, v[130:131]
	s_add_i32 m0, s55, 0x2000
	s_nop 0
	global_load_lds_dwordx4 v[196:197], off
	v_lshl_add_u64 v[196:197], s[28:29], 0, v[134:135]
	s_mov_b32 m0, s40
	s_nop 0
	global_load_lds_dwordx4 v[196:197], off
	s_mov_b32 m0, s41
	s_nop 0
	global_load_lds_dwordx4 v[198:199], off
	s_waitcnt lgkmcnt(0)
	s_barrier
	s_setprio 1
	s_waitcnt lgkmcnt(0)
	v_mfma_f32_16x16x32_bf16 v[60:63], v[150:153], v[182:185], v[60:63]
	v_mfma_f32_16x16x32_bf16 v[52:55], v[158:161], v[182:185], v[52:55]
	v_mfma_f32_16x16x32_bf16 v[44:47], v[150:153], v[190:193], v[44:47]
	v_mfma_f32_16x16x32_bf16 v[36:39], v[158:161], v[190:193], v[36:39]
	v_mfma_f32_16x16x32_bf16 v[28:31], v[150:153], v[206:209], v[28:31]
	v_mfma_f32_16x16x32_bf16 v[20:23], v[158:161], v[206:209], v[20:23]
	v_mfma_f32_16x16x32_bf16 v[12:15], v[150:153], v[214:217], v[12:15]
	v_mfma_f32_16x16x32_bf16 v[4:7], v[158:161], v[214:217], v[4:7]
	v_mfma_f32_16x16x32_bf16 v[60:63], v[154:157], v[186:189], v[60:63]
	v_mfma_f32_16x16x32_bf16 v[52:55], v[162:165], v[186:189], v[52:55]
	v_mfma_f32_16x16x32_bf16 v[44:47], v[154:157], v[202:205], v[44:47]
	v_mfma_f32_16x16x32_bf16 v[36:39], v[162:165], v[202:205], v[36:39]
	v_mfma_f32_16x16x32_bf16 v[28:31], v[154:157], v[210:213], v[28:31]
	v_mfma_f32_16x16x32_bf16 v[20:23], v[162:165], v[210:213], v[20:23]
	v_mfma_f32_16x16x32_bf16 v[12:15], v[154:157], v[218:221], v[12:15]
	v_mfma_f32_16x16x32_bf16 v[4:7], v[162:165], v[218:221], v[4:7]
	s_setprio 0
	s_setprio 1
	v_mfma_f32_16x16x32_bf16 v[56:59], v[166:169], v[182:185], v[56:59]
	v_mfma_f32_16x16x32_bf16 v[48:51], v[174:177], v[182:185], v[48:51]
	v_mfma_f32_16x16x32_bf16 v[40:43], v[166:169], v[190:193], v[40:43]
	v_mfma_f32_16x16x32_bf16 v[32:35], v[174:177], v[190:193], v[32:35]
	v_mfma_f32_16x16x32_bf16 v[24:27], v[166:169], v[206:209], v[24:27]
	v_mfma_f32_16x16x32_bf16 v[16:19], v[174:177], v[206:209], v[16:19]
	v_mfma_f32_16x16x32_bf16 v[8:11], v[166:169], v[214:217], v[8:11]
	v_mfma_f32_16x16x32_bf16 v[0:3], v[174:177], v[214:217], v[0:3]
	v_mfma_f32_16x16x32_bf16 v[56:59], v[170:173], v[186:189], v[56:59]
	v_mfma_f32_16x16x32_bf16 v[48:51], v[178:181], v[186:189], v[48:51]
	v_mfma_f32_16x16x32_bf16 v[40:43], v[170:173], v[202:205], v[40:43]
	v_mfma_f32_16x16x32_bf16 v[32:35], v[178:181], v[202:205], v[32:35]
	v_mfma_f32_16x16x32_bf16 v[24:27], v[170:173], v[210:213], v[24:27]
	v_mfma_f32_16x16x32_bf16 v[16:19], v[178:181], v[210:213], v[16:19]
	v_mfma_f32_16x16x32_bf16 v[8:11], v[170:173], v[218:221], v[8:11]
	v_mfma_f32_16x16x32_bf16 v[0:3], v[178:181], v[218:221], v[0:3]
	s_setprio 0
	s_barrier
	s_add_i32 s55, 0, 0x18000
	v_add_u32_e32 v149, s55, v143
	s_add_i32 s56, 0, 0x1c000
	ds_read_b128 v[150:153], v149
	ds_read_b128 v[154:157], v149 offset:1024
	ds_read_b128 v[158:161], v149 offset:2048
	ds_read_b128 v[162:165], v149 offset:3072
	v_add_u32_e32 v149, s56, v143
	ds_read_b128 v[166:169], v149
	ds_read_b128 v[170:173], v149 offset:1024
	ds_read_b128 v[174:177], v149 offset:2048
	ds_read_b128 v[178:181], v149 offset:3072
	s_add_u32 s28, s28, 0x40000
	s_addc_u32 s29, s29, 0
	s_mov_b32 m0, s42
	v_lshl_add_u64 v[200:201], s[28:29], 0, v[134:135]
	ds_read_b128 v[182:185], v148 offset:32768
	ds_read_b128 v[186:189], v148 offset:33792
	ds_read_b128 v[190:193], v148 offset:34816
	ds_read_b128 v[202:205], v148 offset:35840
	ds_read_b128 v[206:209], v148 offset:36864
	ds_read_b128 v[210:213], v148 offset:37888
	ds_read_b128 v[214:217], v148 offset:38912
	ds_read_b128 v[218:221], v148 offset:39936
	global_load_lds_dwordx4 v[200:201], off
	v_lshl_add_u64 v[200:201], s[28:29], 0, v[132:133]
	s_mov_b32 m0, s43
	s_nop 0
	global_load_lds_dwordx4 v[200:201], off
	s_waitcnt vmcnt(8)
	s_waitcnt lgkmcnt(0)
	s_barrier
	s_setprio 1
	s_waitcnt lgkmcnt(0)
	v_mfma_f32_16x16x32_bf16 v[126:129], v[150:153], v[182:185], v[126:129]
	v_mfma_f32_16x16x32_bf16 v[118:121], v[158:161], v[182:185], v[118:121]
	v_mfma_f32_16x16x32_bf16 v[110:113], v[150:153], v[190:193], v[110:113]
	v_mfma_f32_16x16x32_bf16 v[102:105], v[158:161], v[190:193], v[102:105]
	v_mfma_f32_16x16x32_bf16 v[92:95], v[150:153], v[206:209], v[92:95]
	v_mfma_f32_16x16x32_bf16 v[84:87], v[158:161], v[206:209], v[84:87]
	v_mfma_f32_16x16x32_bf16 v[76:79], v[150:153], v[214:217], v[76:79]
	v_mfma_f32_16x16x32_bf16 v[68:71], v[158:161], v[214:217], v[68:71]
	v_mfma_f32_16x16x32_bf16 v[126:129], v[154:157], v[186:189], v[126:129]
	v_mfma_f32_16x16x32_bf16 v[118:121], v[162:165], v[186:189], v[118:121]
	v_mfma_f32_16x16x32_bf16 v[110:113], v[154:157], v[202:205], v[110:113]
	v_mfma_f32_16x16x32_bf16 v[102:105], v[162:165], v[202:205], v[102:105]
	v_mfma_f32_16x16x32_bf16 v[92:95], v[154:157], v[210:213], v[92:95]
	v_mfma_f32_16x16x32_bf16 v[84:87], v[162:165], v[210:213], v[84:87]
	v_mfma_f32_16x16x32_bf16 v[76:79], v[154:157], v[218:221], v[76:79]
	v_mfma_f32_16x16x32_bf16 v[68:71], v[162:165], v[218:221], v[68:71]
	s_setprio 0
	s_setprio 1
	v_mfma_f32_16x16x32_bf16 v[122:125], v[166:169], v[182:185], v[122:125]
	v_mfma_f32_16x16x32_bf16 v[114:117], v[174:177], v[182:185], v[114:117]
	v_mfma_f32_16x16x32_bf16 v[106:109], v[166:169], v[190:193], v[106:109]
	v_mfma_f32_16x16x32_bf16 v[98:101], v[174:177], v[190:193], v[98:101]
	v_mfma_f32_16x16x32_bf16 v[88:91], v[166:169], v[206:209], v[88:91]
	v_mfma_f32_16x16x32_bf16 v[80:83], v[174:177], v[206:209], v[80:83]
	v_mfma_f32_16x16x32_bf16 v[72:75], v[166:169], v[214:217], v[72:75]
	v_mfma_f32_16x16x32_bf16 v[64:67], v[174:177], v[214:217], v[64:67]
	v_mfma_f32_16x16x32_bf16 v[122:125], v[170:173], v[186:189], v[122:125]
	v_mfma_f32_16x16x32_bf16 v[114:117], v[178:181], v[186:189], v[114:117]
	v_mfma_f32_16x16x32_bf16 v[106:109], v[170:173], v[202:205], v[106:109]
	v_mfma_f32_16x16x32_bf16 v[98:101], v[178:181], v[202:205], v[98:101]
	v_mfma_f32_16x16x32_bf16 v[88:91], v[170:173], v[210:213], v[88:91]
	v_mfma_f32_16x16x32_bf16 v[80:83], v[178:181], v[210:213], v[80:83]
	v_mfma_f32_16x16x32_bf16 v[72:75], v[170:173], v[218:221], v[72:75]
	v_mfma_f32_16x16x32_bf16 v[64:67], v[178:181], v[218:221], v[64:67]
	s_setprio 0
	s_barrier
	s_add_i32 s28, s55, s39
	v_lshl_add_u64 v[140:141], v[140:141], 0, s[64:65]
	s_mov_b32 m0, s28
	ds_read_b128 v[182:185], v148 offset:49152
	ds_read_b128 v[186:189], v148 offset:50176
	ds_read_b128 v[190:193], v148 offset:51200
	ds_read_b128 v[202:205], v148 offset:52224
	ds_read_b128 v[206:209], v148 offset:53248
	ds_read_b128 v[210:213], v148 offset:54272
	ds_read_b128 v[214:217], v148 offset:55296
	ds_read_b128 v[218:221], v148 offset:56320
	global_load_lds_dwordx4 v[140:141], off
	s_add_i32 m0, s28, 0x2000
	s_add_u32 s26, s26, 0x40080
	v_lshl_add_u64 v[140:141], v[194:195], 0, s[64:65]
	s_addc_u32 s27, s27, 0
	s_add_i32 s28, s56, s39
	global_load_lds_dwordx4 v[140:141], off
	v_lshl_add_u64 v[140:141], s[26:27], 0, v[96:97]
	s_mov_b32 m0, s28
	s_nop 0
	global_load_lds_dwordx4 v[140:141], off
	v_lshl_add_u64 v[140:141], s[26:27], 0, v[130:131]
	s_add_i32 m0, s28, 0x2000
	s_nop 0
	global_load_lds_dwordx4 v[140:141], off
	v_lshl_add_u64 v[140:141], v[196:197], 0, s[64:65]
	s_mov_b32 m0, s44
	s_nop 0
	global_load_lds_dwordx4 v[140:141], off
	v_lshl_add_u64 v[140:141], v[198:199], 0, s[64:65]
	s_mov_b32 m0, s45
	s_nop 0
	global_load_lds_dwordx4 v[140:141], off
	s_waitcnt vmcnt(8)
	s_waitcnt lgkmcnt(0)
	s_barrier
	s_setprio 1
	s_waitcnt lgkmcnt(0)
	v_mfma_f32_16x16x32_bf16 v[60:63], v[150:153], v[182:185], v[60:63]
	v_mfma_f32_16x16x32_bf16 v[52:55], v[158:161], v[182:185], v[52:55]
	v_mfma_f32_16x16x32_bf16 v[44:47], v[150:153], v[190:193], v[44:47]
	v_mfma_f32_16x16x32_bf16 v[36:39], v[158:161], v[190:193], v[36:39]
	v_mfma_f32_16x16x32_bf16 v[28:31], v[150:153], v[206:209], v[28:31]
	v_mfma_f32_16x16x32_bf16 v[20:23], v[158:161], v[206:209], v[20:23]
	v_mfma_f32_16x16x32_bf16 v[12:15], v[150:153], v[214:217], v[12:15]
	v_mfma_f32_16x16x32_bf16 v[4:7], v[158:161], v[214:217], v[4:7]
	v_mfma_f32_16x16x32_bf16 v[60:63], v[154:157], v[186:189], v[60:63]
	v_mfma_f32_16x16x32_bf16 v[52:55], v[162:165], v[186:189], v[52:55]
	v_mfma_f32_16x16x32_bf16 v[44:47], v[154:157], v[202:205], v[44:47]
	v_mfma_f32_16x16x32_bf16 v[36:39], v[162:165], v[202:205], v[36:39]
	v_mfma_f32_16x16x32_bf16 v[28:31], v[154:157], v[210:213], v[28:31]
	v_mfma_f32_16x16x32_bf16 v[20:23], v[162:165], v[210:213], v[20:23]
	v_mfma_f32_16x16x32_bf16 v[12:15], v[154:157], v[218:221], v[12:15]
	v_mfma_f32_16x16x32_bf16 v[4:7], v[162:165], v[218:221], v[4:7]
	s_setprio 0
	s_setprio 1
	v_mfma_f32_16x16x32_bf16 v[56:59], v[166:169], v[182:185], v[56:59]
	v_mfma_f32_16x16x32_bf16 v[48:51], v[174:177], v[182:185], v[48:51]
	v_mfma_f32_16x16x32_bf16 v[40:43], v[166:169], v[190:193], v[40:43]
	v_mfma_f32_16x16x32_bf16 v[32:35], v[174:177], v[190:193], v[32:35]
	v_mfma_f32_16x16x32_bf16 v[24:27], v[166:169], v[206:209], v[24:27]
	v_mfma_f32_16x16x32_bf16 v[16:19], v[174:177], v[206:209], v[16:19]
	v_mfma_f32_16x16x32_bf16 v[8:11], v[166:169], v[214:217], v[8:11]
	v_mfma_f32_16x16x32_bf16 v[0:3], v[174:177], v[214:217], v[0:3]
	v_mfma_f32_16x16x32_bf16 v[56:59], v[170:173], v[186:189], v[56:59]
	v_mfma_f32_16x16x32_bf16 v[48:51], v[178:181], v[186:189], v[48:51]
	v_mfma_f32_16x16x32_bf16 v[40:43], v[170:173], v[202:205], v[40:43]
	v_mfma_f32_16x16x32_bf16 v[32:35], v[178:181], v[202:205], v[32:35]
	v_mfma_f32_16x16x32_bf16 v[24:27], v[170:173], v[210:213], v[24:27]
	v_mfma_f32_16x16x32_bf16 v[16:19], v[178:181], v[210:213], v[16:19]
	v_mfma_f32_16x16x32_bf16 v[8:11], v[170:173], v[218:221], v[8:11]
	v_mfma_f32_16x16x32_bf16 v[0:3], v[178:181], v[218:221], v[0:3]
	s_setprio 0
	s_barrier
	s_add_i32 s54, s54, 2
	s_add_u32 s24, s24, 0x100
	s_addc_u32 s25, s25, 0
	s_add_u32 s52, s52, 0x100
	s_addc_u32 s53, s53, 0
	s_cmp_gt_u32 s54, 13
	s_cbranch_scc1 .Lgu_kdone

.Lgu_kdone:
	s_and_b64 vcc, exec, s[10:11]
	s_cbranch_vccz .LBB0_149
	s_barrier

.LBB0_151:
	s_waitcnt vmcnt(0)
	s_and_b32 s15, s47, 1
	v_lshl_add_u32 v150, s15, 10, v146
	ds_read_b32 v152, v150
	v_mov_b32_e32 v154, v122
	v_mov_b32_e32 v155, v126
	v_mov_b32_e32 v126, v123
	v_lshl_or_b32 v140, s23, 7, v144
	s_waitcnt lgkmcnt(0)
	v_pk_mul_f32 v[154:155], v[154:155], v[152:153] op_sel_hi:[1,0]
	v_lshl_add_u32 v149, s22, 8, v142
	v_mul_f32_e32 v122, 0xbfb8aa3b, v155
	v_exp_f32_e32 v122, v122
	v_ashrrev_i32_e32 v141, 31, v140
	s_andn2_b64 vcc, exec, s[2:3]
	v_add_f32_e32 v122, 1.0, v122
	v_rcp_f32_e32 v122, v122
	s_nop 0
	v_mul_f32_e32 v122, v155, v122
	v_mul_f32_e32 v151, v154, v122
	v_pk_mul_f32 v[122:123], v[126:127], v[152:153] op_sel_hi:[1,0]
	s_nop 0
	v_mul_f32_e32 v126, 0xbfb8aa3b, v123
	v_exp_f32_e32 v126, v126
	s_nop 0
	v_add_f32_e32 v126, 1.0, v126
	v_rcp_f32_e32 v126, v126
	s_nop 0
	v_mul_f32_e32 v123, v123, v126
	v_mul_f32_e32 v126, v122, v123
	v_mov_b32_e32 v122, v124
	v_mov_b32_e32 v123, v128
	v_pk_mul_f32 v[122:123], v[122:123], v[152:153] op_sel_hi:[1,0]
	v_mov_b32_e32 v128, v125
	v_mul_f32_e32 v124, 0xbfb8aa3b, v123
	v_exp_f32_e32 v124, v124
	s_nop 0
	v_add_f32_e32 v124, 1.0, v124
	v_rcp_f32_e32 v124, v124
	s_nop 0
	v_mul_f32_e32 v123, v123, v124
	v_mul_f32_e32 v124, v122, v123
	v_pk_mul_f32 v[122:123], v[128:129], v[152:153] op_sel_hi:[1,0]
	s_nop 0
	v_mul_f32_e32 v125, 0xbfb8aa3b, v123
	v_exp_f32_e32 v125, v125
	s_nop 0
	v_add_f32_e32 v125, 1.0, v125
	v_rcp_f32_e32 v125, v125
	s_nop 0
	v_mul_f32_e32 v123, v123, v125
	v_mul_f32_e32 v125, v122, v123
	v_mov_b32_e32 v122, v114
	v_mov_b32_e32 v123, v118
	v_pk_mul_f32 v[122:123], v[122:123], v[152:153] op_sel_hi:[1,0]
	v_mov_b32_e32 v118, v115
	v_mul_f32_e32 v114, 0xbfb8aa3b, v123
	v_exp_f32_e32 v114, v114
	s_nop 0
	v_add_f32_e32 v114, 1.0, v114
	v_rcp_f32_e32 v114, v114
	s_nop 0
	v_mul_f32_e32 v114, v123, v114
	v_mul_f32_e32 v122, v122, v114
	v_pk_mul_f32 v[114:115], v[118:119], v[152:153] op_sel_hi:[1,0]
	s_nop 0
	v_mul_f32_e32 v118, 0xbfb8aa3b, v115
	v_exp_f32_e32 v118, v118
	s_nop 0
	v_add_f32_e32 v118, 1.0, v118
	v_rcp_f32_e32 v118, v118
	s_nop 0
	v_mul_f32_e32 v115, v115, v118
	v_mul_f32_e32 v123, v114, v115
	v_mov_b32_e32 v114, v116
	v_mov_b32_e32 v115, v120
	v_pk_mul_f32 v[114:115], v[114:115], v[152:153] op_sel_hi:[1,0]
	v_mov_b32_e32 v120, v117
	v_mul_f32_e32 v116, 0xbfb8aa3b, v115
	v_exp_f32_e32 v116, v116
	v_cvt_pk_bf16_f32 v118, v151, v126
	v_cvt_pk_bf16_f32 v119, v124, v125
	s_nop 0
	v_add_f32_e32 v116, 1.0, v116
	v_rcp_f32_e32 v116, v116
	s_nop 0
	v_mul_f32_e32 v115, v115, v116
	v_mul_f32_e32 v116, v114, v115
	v_pk_mul_f32 v[114:115], v[120:121], v[152:153] op_sel_hi:[1,0]
	v_cvt_pk_bf16_f32 v120, v122, v123
	s_nop 0
	v_mul_f32_e32 v117, 0xbfb8aa3b, v115
	v_exp_f32_e32 v117, v117
	s_nop 0
	v_add_f32_e32 v117, 1.0, v117
	v_rcp_f32_e32 v117, v117
	s_nop 0
	v_mul_f32_e32 v115, v115, v117
	v_mul_f32_e32 v114, v114, v115
	v_cvt_pk_bf16_f32 v121, v116, v114
	v_mov_b64_e32 v[114:115], s[8:9]
	v_mad_i64_i32 v[122:123], s[22:23], v149, s89, v[114:115]
	v_lshlrev_b64 v[116:117], 1, v[140:141]
	v_lshl_add_u64 v[122:123], v[122:123], 0, v[116:117]
	global_store_dwordx4 v[122:123], v[118:121], off sc1
	s_nop 1
	ds_read_b32 v118, v150 offset:64
	v_mov_b32_e32 v120, v106
	v_mov_b32_e32 v121, v110
	v_mov_b32_e32 v110, v107
	s_waitcnt lgkmcnt(0)
	v_pk_mul_f32 v[120:121], v[120:121], v[118:119] op_sel_hi:[1,0]
	s_nop 0
	v_mul_f32_e32 v106, 0xbfb8aa3b, v121
	v_exp_f32_e32 v106, v106
	s_nop 0
	v_add_f32_e32 v106, 1.0, v106
	v_rcp_f32_e32 v106, v106
	s_nop 0
	v_mul_f32_e32 v106, v121, v106
	v_mul_f32_e32 v119, v120, v106
	v_pk_mul_f32 v[106:107], v[110:111], v[118:119] op_sel_hi:[1,0]
	s_nop 0
	v_mul_f32_e32 v110, 0xbfb8aa3b, v107
	v_exp_f32_e32 v110, v110
	s_nop 0
	v_add_f32_e32 v110, 1.0, v110
	v_rcp_f32_e32 v110, v110
	s_nop 0
	v_mul_f32_e32 v107, v107, v110
	v_mul_f32_e32 v110, v106, v107
	v_mov_b32_e32 v106, v108
	v_mov_b32_e32 v107, v112
	v_pk_mul_f32 v[106:107], v[106:107], v[118:119] op_sel_hi:[1,0]
	v_mov_b32_e32 v112, v109
	v_mul_f32_e32 v108, 0xbfb8aa3b, v107
	v_exp_f32_e32 v108, v108
	s_nop 0
	v_add_f32_e32 v108, 1.0, v108
	v_rcp_f32_e32 v108, v108
	s_nop 0
	v_mul_f32_e32 v107, v107, v108
	v_mul_f32_e32 v108, v106, v107
	v_pk_mul_f32 v[106:107], v[112:113], v[118:119] op_sel_hi:[1,0]
	s_nop 0
	v_mul_f32_e32 v109, 0xbfb8aa3b, v107
	v_exp_f32_e32 v109, v109
	s_nop 0
	v_add_f32_e32 v109, 1.0, v109
	v_rcp_f32_e32 v109, v109
	s_nop 0
	v_mul_f32_e32 v107, v107, v109
	v_mul_f32_e32 v109, v106, v107
	v_mov_b32_e32 v106, v98
	v_mov_b32_e32 v107, v102
	v_pk_mul_f32 v[106:107], v[106:107], v[118:119] op_sel_hi:[1,0]
	v_mov_b32_e32 v102, v99
	v_mul_f32_e32 v98, 0xbfb8aa3b, v107
	v_exp_f32_e32 v98, v98
	s_nop 0
	v_add_f32_e32 v98, 1.0, v98
	v_rcp_f32_e32 v98, v98
	s_nop 0
	v_mul_f32_e32 v98, v107, v98
	v_mul_f32_e32 v106, v106, v98
	v_pk_mul_f32 v[98:99], v[102:103], v[118:119] op_sel_hi:[1,0]
	s_nop 0
	v_mul_f32_e32 v102, 0xbfb8aa3b, v99
	v_exp_f32_e32 v102, v102
	s_nop 0
	v_add_f32_e32 v102, 1.0, v102
	v_rcp_f32_e32 v102, v102
	s_nop 0
	v_mul_f32_e32 v99, v99, v102
	v_mul_f32_e32 v102, v98, v99
	v_mov_b32_e32 v98, v100
	v_mov_b32_e32 v99, v104
	v_pk_mul_f32 v[98:99], v[98:99], v[118:119] op_sel_hi:[1,0]
	v_mov_b32_e32 v104, v101
	v_mul_f32_e32 v100, 0xbfb8aa3b, v99
	v_exp_f32_e32 v100, v100
	s_nop 0
	v_add_f32_e32 v100, 1.0, v100
	v_rcp_f32_e32 v100, v100
	s_nop 0
	v_mul_f32_e32 v99, v99, v100
	v_mul_f32_e32 v103, v98, v99
	v_pk_mul_f32 v[98:99], v[104:105], v[118:119] op_sel_hi:[1,0]
	v_or_b32_e32 v104, 16, v149
	v_mul_f32_e32 v100, 0xbfb8aa3b, v99
	v_exp_f32_e32 v100, v100
	s_nop 0
	v_add_f32_e32 v100, 1.0, v100
	v_rcp_f32_e32 v100, v100
	s_nop 0
	v_mul_f32_e32 v99, v99, v100
	v_mul_f32_e32 v101, v98, v99
	v_cvt_pk_bf16_f32 v98, v119, v110
	v_cvt_pk_bf16_f32 v99, v108, v109
	v_cvt_pk_bf16_f32 v100, v106, v102
	v_cvt_pk_bf16_f32 v101, v103, v101
	v_mad_i64_i32 v[102:103], s[22:23], v104, s89, v[114:115]
	v_lshl_add_u64 v[102:103], v[102:103], 0, v[116:117]
	global_store_dwordx4 v[102:103], v[98:101], off sc1
	s_nop 1
	ds_read_b32 v98, v150 offset:128
	v_mov_b32_e32 v100, v88
	v_mov_b32_e32 v101, v92
	v_mov_b32_e32 v92, v89
	s_waitcnt lgkmcnt(0)
	v_pk_mul_f32 v[100:101], v[100:101], v[98:99] op_sel_hi:[1,0]
	s_nop 0
	v_mul_f32_e32 v88, 0xbfb8aa3b, v101
	v_exp_f32_e32 v88, v88
	s_nop 0
	v_add_f32_e32 v88, 1.0, v88
	v_rcp_f32_e32 v88, v88
	s_nop 0
	v_mul_f32_e32 v88, v101, v88
	v_mul_f32_e32 v99, v100, v88
	v_pk_mul_f32 v[88:89], v[92:93], v[98:99] op_sel_hi:[1,0]
	s_nop 0
	v_mul_f32_e32 v92, 0xbfb8aa3b, v89
	v_exp_f32_e32 v92, v92
	s_nop 0
	v_add_f32_e32 v92, 1.0, v92
	v_rcp_f32_e32 v92, v92
	s_nop 0
	v_mul_f32_e32 v89, v89, v92
	v_mul_f32_e32 v92, v88, v89
	v_mov_b32_e32 v88, v90
	v_mov_b32_e32 v89, v94
	v_pk_mul_f32 v[88:89], v[88:89], v[98:99] op_sel_hi:[1,0]
	v_mov_b32_e32 v94, v91
	v_mul_f32_e32 v90, 0xbfb8aa3b, v89
	v_exp_f32_e32 v90, v90
	s_nop 0
	v_add_f32_e32 v90, 1.0, v90
	v_rcp_f32_e32 v90, v90
	s_nop 0
	v_mul_f32_e32 v89, v89, v90
	v_mul_f32_e32 v90, v88, v89
	v_pk_mul_f32 v[88:89], v[94:95], v[98:99] op_sel_hi:[1,0]
	s_nop 0
	v_mul_f32_e32 v91, 0xbfb8aa3b, v89
	v_exp_f32_e32 v91, v91
	s_nop 0
	v_add_f32_e32 v91, 1.0, v91
	v_rcp_f32_e32 v91, v91
	s_nop 0
	v_mul_f32_e32 v89, v89, v91
	v_mul_f32_e32 v91, v88, v89
	v_mov_b32_e32 v88, v80
	v_mov_b32_e32 v89, v84
	v_pk_mul_f32 v[88:89], v[88:89], v[98:99] op_sel_hi:[1,0]
	v_mov_b32_e32 v84, v81
	v_mul_f32_e32 v80, 0xbfb8aa3b, v89
	v_exp_f32_e32 v80, v80
	s_nop 0
	v_add_f32_e32 v80, 1.0, v80
	v_rcp_f32_e32 v80, v80
	s_nop 0
	v_mul_f32_e32 v80, v89, v80
	v_mul_f32_e32 v88, v88, v80
	v_pk_mul_f32 v[80:81], v[84:85], v[98:99] op_sel_hi:[1,0]
	s_nop 0
	v_mul_f32_e32 v84, 0xbfb8aa3b, v81
	v_exp_f32_e32 v84, v84
	s_nop 0
	v_add_f32_e32 v84, 1.0, v84
	v_rcp_f32_e32 v84, v84
	s_nop 0
	v_mul_f32_e32 v81, v81, v84
	v_mul_f32_e32 v84, v80, v81
	v_mov_b32_e32 v80, v82
	v_mov_b32_e32 v81, v86
	v_pk_mul_f32 v[80:81], v[80:81], v[98:99] op_sel_hi:[1,0]
	v_mov_b32_e32 v86, v83
	v_mul_f32_e32 v82, 0xbfb8aa3b, v81
	v_exp_f32_e32 v82, v82
	s_nop 0
	v_add_f32_e32 v82, 1.0, v82
	v_rcp_f32_e32 v82, v82
	s_nop 0
	v_mul_f32_e32 v81, v81, v82
	v_mul_f32_e32 v85, v80, v81
	v_pk_mul_f32 v[80:81], v[86:87], v[98:99] op_sel_hi:[1,0]
	v_or_b32_e32 v86, 32, v149
	v_mul_f32_e32 v82, 0xbfb8aa3b, v81
	v_exp_f32_e32 v82, v82
	s_nop 0
	v_add_f32_e32 v82, 1.0, v82
	v_rcp_f32_e32 v82, v82
	s_nop 0
	v_mul_f32_e32 v81, v81, v82
	v_mul_f32_e32 v83, v80, v81
	v_cvt_pk_bf16_f32 v80, v99, v92
	v_cvt_pk_bf16_f32 v81, v90, v91
	v_cvt_pk_bf16_f32 v82, v88, v84
	v_cvt_pk_bf16_f32 v83, v85, v83
	v_mad_i64_i32 v[84:85], s[22:23], v86, s89, v[114:115]
	v_lshl_add_u64 v[84:85], v[84:85], 0, v[116:117]
	global_store_dwordx4 v[84:85], v[80:83], off sc1
	s_nop 1
	ds_read_b32 v80, v150 offset:192
	v_mov_b32_e32 v82, v72
	v_mov_b32_e32 v83, v76
	v_mov_b32_e32 v76, v73
	s_waitcnt lgkmcnt(0)
	v_pk_mul_f32 v[82:83], v[82:83], v[80:81] op_sel_hi:[1,0]
	s_nop 0
	v_mul_f32_e32 v72, 0xbfb8aa3b, v83
	v_exp_f32_e32 v72, v72
	s_nop 0
	v_add_f32_e32 v72, 1.0, v72
	v_rcp_f32_e32 v72, v72
	s_nop 0
	v_mul_f32_e32 v72, v83, v72
	v_mul_f32_e32 v81, v82, v72
	v_pk_mul_f32 v[72:73], v[76:77], v[80:81] op_sel_hi:[1,0]
	s_nop 0
	v_mul_f32_e32 v76, 0xbfb8aa3b, v73
	v_exp_f32_e32 v76, v76
	s_nop 0
	v_add_f32_e32 v76, 1.0, v76
	v_rcp_f32_e32 v76, v76
	s_nop 0
	v_mul_f32_e32 v73, v73, v76
	v_mul_f32_e32 v76, v72, v73
	v_mov_b32_e32 v72, v74
	v_mov_b32_e32 v73, v78
	v_pk_mul_f32 v[72:73], v[72:73], v[80:81] op_sel_hi:[1,0]
	v_mov_b32_e32 v78, v75
	v_mul_f32_e32 v74, 0xbfb8aa3b, v73
	v_exp_f32_e32 v74, v74
	s_nop 0
	v_add_f32_e32 v74, 1.0, v74
	v_rcp_f32_e32 v74, v74
	s_nop 0
	v_mul_f32_e32 v73, v73, v74
	v_mul_f32_e32 v74, v72, v73
	v_pk_mul_f32 v[72:73], v[78:79], v[80:81] op_sel_hi:[1,0]
	s_nop 0
	v_mul_f32_e32 v75, 0xbfb8aa3b, v73
	v_exp_f32_e32 v75, v75
	s_nop 0
	v_add_f32_e32 v75, 1.0, v75
	v_rcp_f32_e32 v75, v75
	s_nop 0
	v_mul_f32_e32 v73, v73, v75
	v_mul_f32_e32 v75, v72, v73
	v_mov_b32_e32 v72, v64
	v_mov_b32_e32 v73, v68
	v_pk_mul_f32 v[72:73], v[72:73], v[80:81] op_sel_hi:[1,0]
	v_mov_b32_e32 v68, v65
	v_mul_f32_e32 v64, 0xbfb8aa3b, v73
	v_exp_f32_e32 v64, v64
	s_nop 0
	v_add_f32_e32 v64, 1.0, v64
	v_rcp_f32_e32 v64, v64
	s_nop 0
	v_mul_f32_e32 v64, v73, v64
	v_mul_f32_e32 v72, v72, v64
	v_pk_mul_f32 v[64:65], v[68:69], v[80:81] op_sel_hi:[1,0]
	s_nop 0
	v_mul_f32_e32 v68, 0xbfb8aa3b, v65
	v_exp_f32_e32 v68, v68
	s_nop 0
	v_add_f32_e32 v68, 1.0, v68
	v_rcp_f32_e32 v68, v68
	s_nop 0
	v_mul_f32_e32 v65, v65, v68
	v_mul_f32_e32 v68, v64, v65
	v_mov_b32_e32 v64, v66
	v_mov_b32_e32 v65, v70
	v_pk_mul_f32 v[64:65], v[64:65], v[80:81] op_sel_hi:[1,0]
	v_mov_b32_e32 v70, v67
	v_mul_f32_e32 v66, 0xbfb8aa3b, v65
	v_exp_f32_e32 v66, v66
	s_nop 0
	v_add_f32_e32 v66, 1.0, v66
	v_rcp_f32_e32 v66, v66
	s_nop 0
	v_mul_f32_e32 v65, v65, v66
	v_mul_f32_e32 v69, v64, v65
	v_pk_mul_f32 v[64:65], v[70:71], v[80:81] op_sel_hi:[1,0]
	v_or_b32_e32 v70, 48, v149
	v_mul_f32_e32 v66, 0xbfb8aa3b, v65
	v_exp_f32_e32 v66, v66
	s_nop 0
	v_add_f32_e32 v66, 1.0, v66
	v_rcp_f32_e32 v66, v66
	s_nop 0
	v_mul_f32_e32 v65, v65, v66
	v_mul_f32_e32 v67, v64, v65
	v_cvt_pk_bf16_f32 v64, v81, v76
	v_cvt_pk_bf16_f32 v65, v74, v75
	v_cvt_pk_bf16_f32 v66, v72, v68
	v_cvt_pk_bf16_f32 v67, v69, v67
	v_mad_i64_i32 v[68:69], s[22:23], v70, s89, v[114:115]
	v_lshl_add_u64 v[68:69], v[68:69], 0, v[116:117]
	global_store_dwordx4 v[68:69], v[64:67], off sc1
	s_nop 1
	ds_read_b32 v64, v150 offset:512
	v_add_u32_e32 v65, 0x80, v149
	v_mov_b32_e32 v66, v56
	v_mov_b32_e32 v67, v60
	v_mov_b32_e32 v60, v57
	s_waitcnt lgkmcnt(0)
	v_pk_mul_f32 v[66:67], v[66:67], v[64:65] op_sel_hi:[1,0]
	s_nop 0
	v_mul_f32_e32 v56, 0xbfb8aa3b, v67
	v_exp_f32_e32 v56, v56
	s_nop 0
	v_add_f32_e32 v56, 1.0, v56
	v_rcp_f32_e32 v56, v56
	s_nop 0
	v_mul_f32_e32 v56, v67, v56
	v_mul_f32_e32 v66, v66, v56
	v_pk_mul_f32 v[56:57], v[60:61], v[64:65] op_sel_hi:[1,0]
	s_nop 0
	v_mul_f32_e32 v60, 0xbfb8aa3b, v57
	v_exp_f32_e32 v60, v60
	s_nop 0
	v_add_f32_e32 v60, 1.0, v60
	v_rcp_f32_e32 v60, v60
	s_nop 0
	v_mul_f32_e32 v57, v57, v60
	v_mul_f32_e32 v60, v56, v57
	v_mov_b32_e32 v56, v58
	v_mov_b32_e32 v57, v62
	v_pk_mul_f32 v[56:57], v[56:57], v[64:65] op_sel_hi:[1,0]
	v_mov_b32_e32 v62, v59
	v_mul_f32_e32 v58, 0xbfb8aa3b, v57
	v_exp_f32_e32 v58, v58
	s_nop 0
	v_add_f32_e32 v58, 1.0, v58
	v_rcp_f32_e32 v58, v58
	s_nop 0
	v_mul_f32_e32 v57, v57, v58
	v_mul_f32_e32 v58, v56, v57
	v_pk_mul_f32 v[56:57], v[62:63], v[64:65] op_sel_hi:[1,0]
	s_nop 0
	v_mul_f32_e32 v59, 0xbfb8aa3b, v57
	v_exp_f32_e32 v59, v59
	s_nop 0
	v_add_f32_e32 v59, 1.0, v59
	v_rcp_f32_e32 v59, v59
	s_nop 0
	v_mul_f32_e32 v57, v57, v59
	v_mul_f32_e32 v59, v56, v57
	v_mov_b32_e32 v56, v48
	v_mov_b32_e32 v57, v52
	v_pk_mul_f32 v[56:57], v[56:57], v[64:65] op_sel_hi:[1,0]
	v_mov_b32_e32 v52, v49
	v_mul_f32_e32 v48, 0xbfb8aa3b, v57
	v_exp_f32_e32 v48, v48
	s_nop 0
	v_add_f32_e32 v48, 1.0, v48
	v_rcp_f32_e32 v48, v48
	s_nop 0
	v_mul_f32_e32 v48, v57, v48
	v_mul_f32_e32 v56, v56, v48
	v_pk_mul_f32 v[48:49], v[52:53], v[64:65] op_sel_hi:[1,0]
	s_nop 0
	v_mul_f32_e32 v52, 0xbfb8aa3b, v49
	v_exp_f32_e32 v52, v52
	s_nop 0
	v_add_f32_e32 v52, 1.0, v52
	v_rcp_f32_e32 v52, v52
	s_nop 0
	v_mul_f32_e32 v49, v49, v52
	v_mul_f32_e32 v52, v48, v49
	v_mov_b32_e32 v48, v50
	v_mov_b32_e32 v49, v54
	v_pk_mul_f32 v[48:49], v[48:49], v[64:65] op_sel_hi:[1,0]
	v_mov_b32_e32 v54, v51
	v_mul_f32_e32 v50, 0xbfb8aa3b, v49
	v_exp_f32_e32 v50, v50
	s_nop 0
	v_add_f32_e32 v50, 1.0, v50
	v_rcp_f32_e32 v50, v50
	s_nop 0
	v_mul_f32_e32 v49, v49, v50
	v_mul_f32_e32 v53, v48, v49
	v_pk_mul_f32 v[48:49], v[54:55], v[64:65] op_sel_hi:[1,0]
	s_nop 0
	v_mul_f32_e32 v50, 0xbfb8aa3b, v49
	v_exp_f32_e32 v50, v50
	s_nop 0
	v_add_f32_e32 v50, 1.0, v50
	v_rcp_f32_e32 v50, v50
	s_nop 0
	v_mul_f32_e32 v49, v49, v50
	v_mul_f32_e32 v51, v48, v49
	v_cvt_pk_bf16_f32 v48, v66, v60
	v_cvt_pk_bf16_f32 v49, v58, v59
	v_cvt_pk_bf16_f32 v50, v56, v52
	v_cvt_pk_bf16_f32 v51, v53, v51
	v_mad_i64_i32 v[52:53], s[22:23], v65, s89, v[114:115]
	v_lshl_add_u64 v[52:53], v[52:53], 0, v[116:117]
	global_store_dwordx4 v[52:53], v[48:51], off sc1
	s_nop 1
	ds_read_b32 v48, v150 offset:576
	v_mov_b32_e32 v50, v40
	v_mov_b32_e32 v51, v44
	v_mov_b32_e32 v44, v41
	s_waitcnt lgkmcnt(0)
	v_pk_mul_f32 v[50:51], v[50:51], v[48:49] op_sel_hi:[1,0]
	s_nop 0
	v_mul_f32_e32 v40, 0xbfb8aa3b, v51
	v_exp_f32_e32 v40, v40
	s_nop 0
	v_add_f32_e32 v40, 1.0, v40
	v_rcp_f32_e32 v40, v40
	s_nop 0
	v_mul_f32_e32 v40, v51, v40
	v_mul_f32_e32 v49, v50, v40
	v_pk_mul_f32 v[40:41], v[44:45], v[48:49] op_sel_hi:[1,0]
	s_nop 0
	v_mul_f32_e32 v44, 0xbfb8aa3b, v41
	v_exp_f32_e32 v44, v44
	s_nop 0
	v_add_f32_e32 v44, 1.0, v44
	v_rcp_f32_e32 v44, v44
	s_nop 0
	v_mul_f32_e32 v41, v41, v44
	v_mul_f32_e32 v44, v40, v41
	v_mov_b32_e32 v40, v42
	v_mov_b32_e32 v41, v46
	v_pk_mul_f32 v[40:41], v[40:41], v[48:49] op_sel_hi:[1,0]
	v_mov_b32_e32 v46, v43
	v_mul_f32_e32 v42, 0xbfb8aa3b, v41
	v_exp_f32_e32 v42, v42
	s_nop 0
	v_add_f32_e32 v42, 1.0, v42
	v_rcp_f32_e32 v42, v42
	s_nop 0
	v_mul_f32_e32 v41, v41, v42
	v_mul_f32_e32 v42, v40, v41
	v_pk_mul_f32 v[40:41], v[46:47], v[48:49] op_sel_hi:[1,0]
	s_nop 0
	v_mul_f32_e32 v43, 0xbfb8aa3b, v41
	v_exp_f32_e32 v43, v43
	s_nop 0
	v_add_f32_e32 v43, 1.0, v43
	v_rcp_f32_e32 v43, v43
	s_nop 0
	v_mul_f32_e32 v41, v41, v43
	v_mul_f32_e32 v43, v40, v41
	v_mov_b32_e32 v40, v32
	v_mov_b32_e32 v41, v36
	v_pk_mul_f32 v[40:41], v[40:41], v[48:49] op_sel_hi:[1,0]
	v_mov_b32_e32 v36, v33
	v_mul_f32_e32 v32, 0xbfb8aa3b, v41
	v_exp_f32_e32 v32, v32
	s_nop 0
	v_add_f32_e32 v32, 1.0, v32
	v_rcp_f32_e32 v32, v32
	s_nop 0
	v_mul_f32_e32 v32, v41, v32
	v_mul_f32_e32 v40, v40, v32
	v_pk_mul_f32 v[32:33], v[36:37], v[48:49] op_sel_hi:[1,0]
	s_nop 0
	v_mul_f32_e32 v36, 0xbfb8aa3b, v33
	v_exp_f32_e32 v36, v36
	s_nop 0
	v_add_f32_e32 v36, 1.0, v36
	v_rcp_f32_e32 v36, v36
	s_nop 0
	v_mul_f32_e32 v33, v33, v36
	v_mul_f32_e32 v36, v32, v33
	v_mov_b32_e32 v32, v34
	v_mov_b32_e32 v33, v38
	v_pk_mul_f32 v[32:33], v[32:33], v[48:49] op_sel_hi:[1,0]
	v_mov_b32_e32 v38, v35
	v_mul_f32_e32 v34, 0xbfb8aa3b, v33
	v_exp_f32_e32 v34, v34
	s_nop 0
	v_add_f32_e32 v34, 1.0, v34
	v_rcp_f32_e32 v34, v34
	s_nop 0
	v_mul_f32_e32 v33, v33, v34
	v_mul_f32_e32 v37, v32, v33
	v_pk_mul_f32 v[32:33], v[38:39], v[48:49] op_sel_hi:[1,0]
	v_add_u32_e32 v38, 0x90, v149
	v_mul_f32_e32 v34, 0xbfb8aa3b, v33
	v_exp_f32_e32 v34, v34
	s_nop 0
	v_add_f32_e32 v34, 1.0, v34
	v_rcp_f32_e32 v34, v34
	s_nop 0
	v_mul_f32_e32 v33, v33, v34
	v_mul_f32_e32 v35, v32, v33
	v_cvt_pk_bf16_f32 v32, v49, v44
	v_cvt_pk_bf16_f32 v33, v42, v43
	v_cvt_pk_bf16_f32 v34, v40, v36
	v_cvt_pk_bf16_f32 v35, v37, v35
	v_mad_i64_i32 v[36:37], s[22:23], v38, s89, v[114:115]
	v_lshl_add_u64 v[36:37], v[36:37], 0, v[116:117]
	global_store_dwordx4 v[36:37], v[32:35], off sc1
	s_nop 1
	ds_read_b32 v32, v150 offset:640
	v_mov_b32_e32 v34, v24
	v_mov_b32_e32 v35, v28
	v_mov_b32_e32 v28, v25
	s_waitcnt lgkmcnt(0)
	v_pk_mul_f32 v[34:35], v[34:35], v[32:33] op_sel_hi:[1,0]
	s_nop 0
	v_mul_f32_e32 v24, 0xbfb8aa3b, v35
	v_exp_f32_e32 v24, v24
	s_nop 0
	v_add_f32_e32 v24, 1.0, v24
	v_rcp_f32_e32 v24, v24
	s_nop 0
	v_mul_f32_e32 v24, v35, v24
	v_mul_f32_e32 v33, v34, v24
	v_pk_mul_f32 v[24:25], v[28:29], v[32:33] op_sel_hi:[1,0]
	s_nop 0
	v_mul_f32_e32 v28, 0xbfb8aa3b, v25
	v_exp_f32_e32 v28, v28
	s_nop 0
	v_add_f32_e32 v28, 1.0, v28
	v_rcp_f32_e32 v28, v28
	s_nop 0
	v_mul_f32_e32 v25, v25, v28
	v_mul_f32_e32 v28, v24, v25
	v_mov_b32_e32 v24, v26
	v_mov_b32_e32 v25, v30
	v_pk_mul_f32 v[24:25], v[24:25], v[32:33] op_sel_hi:[1,0]
	v_mov_b32_e32 v30, v27
	v_mul_f32_e32 v26, 0xbfb8aa3b, v25
	v_exp_f32_e32 v26, v26
	s_nop 0
	v_add_f32_e32 v26, 1.0, v26
	v_rcp_f32_e32 v26, v26
	s_nop 0
	v_mul_f32_e32 v25, v25, v26
	v_mul_f32_e32 v26, v24, v25
	v_pk_mul_f32 v[24:25], v[30:31], v[32:33] op_sel_hi:[1,0]
	s_nop 0
	v_mul_f32_e32 v27, 0xbfb8aa3b, v25
	v_exp_f32_e32 v27, v27
	s_nop 0
	v_add_f32_e32 v27, 1.0, v27
	v_rcp_f32_e32 v27, v27
	s_nop 0
	v_mul_f32_e32 v25, v25, v27
	v_mul_f32_e32 v27, v24, v25
	v_mov_b32_e32 v24, v16
	v_mov_b32_e32 v25, v20
	v_pk_mul_f32 v[24:25], v[24:25], v[32:33] op_sel_hi:[1,0]
	v_mov_b32_e32 v20, v17
	v_mul_f32_e32 v16, 0xbfb8aa3b, v25
	v_exp_f32_e32 v16, v16
	s_nop 0
	v_add_f32_e32 v16, 1.0, v16
	v_rcp_f32_e32 v16, v16
	s_nop 0
	v_mul_f32_e32 v16, v25, v16
	v_mul_f32_e32 v24, v24, v16
	v_pk_mul_f32 v[16:17], v[20:21], v[32:33] op_sel_hi:[1,0]
	s_nop 0
	v_mul_f32_e32 v20, 0xbfb8aa3b, v17
	v_exp_f32_e32 v20, v20
	s_nop 0
	v_add_f32_e32 v20, 1.0, v20
	v_rcp_f32_e32 v20, v20
	s_nop 0
	v_mul_f32_e32 v17, v17, v20
	v_mul_f32_e32 v20, v16, v17
	v_mov_b32_e32 v16, v18
	v_mov_b32_e32 v17, v22
	v_pk_mul_f32 v[16:17], v[16:17], v[32:33] op_sel_hi:[1,0]
	v_mov_b32_e32 v22, v19
	v_mul_f32_e32 v18, 0xbfb8aa3b, v17
	v_exp_f32_e32 v18, v18
	s_nop 0
	v_add_f32_e32 v18, 1.0, v18
	v_rcp_f32_e32 v18, v18
	s_nop 0
	v_mul_f32_e32 v17, v17, v18
	v_mul_f32_e32 v21, v16, v17
	v_pk_mul_f32 v[16:17], v[22:23], v[32:33] op_sel_hi:[1,0]
	v_add_u32_e32 v22, 0xa0, v149
	v_mul_f32_e32 v18, 0xbfb8aa3b, v17
	v_exp_f32_e32 v18, v18
	s_nop 0
	v_add_f32_e32 v18, 1.0, v18
	v_rcp_f32_e32 v18, v18
	s_nop 0
	v_mul_f32_e32 v17, v17, v18
	v_mul_f32_e32 v19, v16, v17
	v_cvt_pk_bf16_f32 v16, v33, v28
	v_cvt_pk_bf16_f32 v17, v26, v27
	v_cvt_pk_bf16_f32 v18, v24, v20
	v_cvt_pk_bf16_f32 v19, v21, v19
	v_mad_i64_i32 v[20:21], s[22:23], v22, s89, v[114:115]
	v_lshl_add_u64 v[20:21], v[20:21], 0, v[116:117]
	global_store_dwordx4 v[20:21], v[16:19], off sc1
	s_nop 1
	ds_read_b32 v16, v150 offset:704
	v_mov_b32_e32 v18, v8
	v_mov_b32_e32 v19, v12
	v_mov_b32_e32 v12, v9
	s_waitcnt lgkmcnt(0)
	v_pk_mul_f32 v[18:19], v[18:19], v[16:17] op_sel_hi:[1,0]
	s_nop 0
	v_mul_f32_e32 v8, 0xbfb8aa3b, v19
	v_exp_f32_e32 v8, v8
	s_nop 0
	v_add_f32_e32 v8, 1.0, v8
	v_rcp_f32_e32 v8, v8
	s_nop 0
	v_mul_f32_e32 v8, v19, v8
	v_mul_f32_e32 v17, v18, v8
	v_pk_mul_f32 v[8:9], v[12:13], v[16:17] op_sel_hi:[1,0]
	s_nop 0
	v_mul_f32_e32 v12, 0xbfb8aa3b, v9
	v_exp_f32_e32 v12, v12
	s_nop 0
	v_add_f32_e32 v12, 1.0, v12
	v_rcp_f32_e32 v12, v12
	s_nop 0
	v_mul_f32_e32 v9, v9, v12
	v_mul_f32_e32 v12, v8, v9
	v_mov_b32_e32 v8, v10
	v_mov_b32_e32 v9, v14
	v_pk_mul_f32 v[8:9], v[8:9], v[16:17] op_sel_hi:[1,0]
	v_mov_b32_e32 v14, v11
	v_mul_f32_e32 v10, 0xbfb8aa3b, v9
	v_exp_f32_e32 v10, v10
	s_nop 0
	v_add_f32_e32 v10, 1.0, v10
	v_rcp_f32_e32 v10, v10
	s_nop 0
	v_mul_f32_e32 v9, v9, v10
	v_mul_f32_e32 v10, v8, v9
	v_pk_mul_f32 v[8:9], v[14:15], v[16:17] op_sel_hi:[1,0]
	s_nop 0
	v_mul_f32_e32 v11, 0xbfb8aa3b, v9
	v_exp_f32_e32 v11, v11
	s_nop 0
	v_add_f32_e32 v11, 1.0, v11
	v_rcp_f32_e32 v11, v11
	s_nop 0
	v_mul_f32_e32 v9, v9, v11
	v_mul_f32_e32 v11, v8, v9
	v_mov_b32_e32 v8, v0
	v_mov_b32_e32 v9, v4
	v_pk_mul_f32 v[8:9], v[8:9], v[16:17] op_sel_hi:[1,0]
	v_mov_b32_e32 v4, v1
	v_mul_f32_e32 v0, 0xbfb8aa3b, v9
	v_exp_f32_e32 v0, v0
	s_nop 0
	v_add_f32_e32 v0, 1.0, v0
	v_rcp_f32_e32 v0, v0
	s_nop 0
	v_mul_f32_e32 v0, v9, v0
	v_mul_f32_e32 v8, v8, v0
	v_pk_mul_f32 v[0:1], v[4:5], v[16:17] op_sel_hi:[1,0]
	s_nop 0
	v_mul_f32_e32 v4, 0xbfb8aa3b, v1
	v_exp_f32_e32 v4, v4
	s_nop 0
	v_add_f32_e32 v4, 1.0, v4
	v_rcp_f32_e32 v4, v4
	s_nop 0
	v_mul_f32_e32 v1, v1, v4
	v_mul_f32_e32 v4, v0, v1
	v_mov_b32_e32 v0, v2
	v_mov_b32_e32 v1, v6
	v_pk_mul_f32 v[0:1], v[0:1], v[16:17] op_sel_hi:[1,0]
	v_mov_b32_e32 v6, v3
	v_mul_f32_e32 v2, 0xbfb8aa3b, v1
	v_exp_f32_e32 v2, v2
	s_nop 0
	v_add_f32_e32 v2, 1.0, v2
	v_rcp_f32_e32 v2, v2
	s_nop 0
	v_mul_f32_e32 v1, v1, v2
	v_mul_f32_e32 v5, v0, v1
	v_pk_mul_f32 v[0:1], v[6:7], v[16:17] op_sel_hi:[1,0]
	v_add_u32_e32 v6, 0xb0, v149
	v_mul_f32_e32 v2, 0xbfb8aa3b, v1
	v_exp_f32_e32 v2, v2
	s_nop 0
	v_add_f32_e32 v2, 1.0, v2
	v_rcp_f32_e32 v2, v2
	s_nop 0
	v_mul_f32_e32 v1, v1, v2
	v_mul_f32_e32 v3, v0, v1
	v_cvt_pk_bf16_f32 v0, v17, v12
	v_cvt_pk_bf16_f32 v1, v10, v11
	v_cvt_pk_bf16_f32 v2, v8, v4
	v_cvt_pk_bf16_f32 v3, v5, v3
	v_mad_i64_i32 v[4:5], s[22:23], v6, s89, v[114:115]
	v_lshl_add_u64 v[4:5], v[4:5], 0, v[116:117]
	global_store_dwordx4 v[4:5], v[0:3], off sc1
	s_nop 1
	s_mov_b64 s[22:23], -1
	s_cbranch_vccnz .LBB0_142
	s_andn2_b64 vcc, exec, s[6:7]
	s_cbranch_vccnz .LBB0_141
	s_barrier
	s_branch .LBB0_141
